# P1 load segments: A-fragment LDS reads issued ahead of the scalar / 64-bit address arithmetic of the LDS-DMA stage loads
# baseline (speedup 1.0000x reference)
; #define PG8_LAS __attribute__((address_space(3)))
; #define PG8_STAGE(bufoff, gbase, voff) do { _Pragma("unroll") for (int _i = 0; _i < 2; ++_i) \
;         __builtin_amdgcn_global_load_lds((const unsigned*)((const char*)(gbase) + (voff)[_i]), (PG8_LAS unsigned*)(lds + (bufoff) + ldsw + _i * 8192), 16, 0, 0); } while (0)
; #define PG8_WAIT_V(n) asm volatile("s_waitcnt vmcnt(" #n ")" ::: "memory")
; #define PG8_WAIT_L(n) asm volatile("s_waitcnt lgkmcnt(" #n ")" ::: "memory")
; template <class Epi, class Sched, bool ALIGN_EPI = false, bool SP2 = false, bool RS = false, bool BPRE = false>
; __device__ __forceinline__ void gemm_phase(PG8_LAS unsigned char* lds, const Gemm g, const Sched& S, const Epi& E, const float* rs_ss = nullptr, PG8_LAS float* rs_tab = nullptr) {
;     ...
;         const char* nA = has_next ? (const char*)g.A + (size_t)nxt.pm * tstep : cA; const char* nB = has_next ? (const char*)g.Bt + (size_t)nxt.pn * tstep : cB;
;         for (int t = 0; t < nt; t += 2) {
;             const bool last = (t == nt - 2);
;             if constexpr (RS) { if (t == 16 || t == 32) { const PG8_LAS float* tp = rs_tab + (ui & 1) * 768 + (t == 32 ? 256 : 0);
;                 _Pragma("unroll") for (int a = 0; a < 2; ++a) _Pragma("unroll") for (int m = 0; m < 4; ++m) { const float f = tp[a * HALF + wr * 64 + m * 16 + fr];
;                     _Pragma("unroll") for (int b = 0; b < 2; ++b) _Pragma("unroll") for (int n = 0; n < 2; ++n) acc[a][b][m][n] = acc[a][b][m][n] * f; } } }
;             const char* a1 = cA + (size_t)(t + 1) * kstep;
;             const char* a2 = last ? nA : cA + (size_t)(t + 2) * kstep; const char* b2 = last ? nB : cB + (size_t)(t + 2) * kstep;
;             const char* a3 = a2 + kstep; const char* b3 = b2 + kstep;
;             if (last && has_next) S.a_ready(nxt);
;             if constexpr (SP2) {
;             PG8_LDB(B0, 0, 0); PG8_LDB(B1, 0, 1); PG8_SCHED; PG8_LDA(At, 0, 0); PG8_STAGE(PG8_SA(1, 1), a1 + hstep, voffA);
;             PG8_WAIT_V(8); PG8_WAIT_L(0); PG8_BAR; PG8_MMA(0, 0, At, B0); PG8_MMA(0, 1, At, B1); PG8_BAR; PG8_SCHED;
;             PG8_LDA(At, 0, 1); PG8_STAGE(PG8_SB(0, 0), b2, voffB); PG8_STAGE(PG8_SB(0, 1), b2 + hstep, voffB); PG8_STAGE(PG8_SA(0, 0), a2, voffA);
;             PG8_WAIT_V(8); PG8_WAIT_L(0); PG8_BAR; PG8_MMA(1, 0, At, B0); PG8_MMA(1, 1, At, B1); PG8_BAR; PG8_SCHED;
.LBB0_195:
	s_ashr_i32 s19, s18, 31
	s_lshl_b64 s[20:21], s[18:19], 20
	s_add_u32 s20, s30, s20
	s_addc_u32 s21, s31, s21
	s_and_b64 s[44:45], s[6:7], exec
	s_cselect_b32 s5, s21, s57
	s_cselect_b32 s19, s20, s56
	s_ashr_i32 s17, s16, 31
	s_lshl_b64 s[44:45], s[16:17], 20
	s_add_u32 s44, s24, s44
	s_addc_u32 s45, s25, s45
	s_and_b64 s[60:61], s[6:7], exec
	s_cselect_b32 s17, s45, s59
	s_cselect_b32 s47, s44, s58
	s_add_u32 s56, s56, 0x84000
	s_addc_u32 s57, s57, 0
	s_add_u32 s87, s58, 0x8000
	s_addc_u32 s88, s59, 0
	s_mov_b32 s89, -2
	s_waitcnt lgkmcnt(0)
	ds_read_b128 v[130:133], v161
	ds_read_b128 v[134:137], v161 offset:1024
	ds_read_b128 v[152:155], v161 offset:2048
	ds_read_b128 v[156:159], v161 offset:3072
	ds_read_b128 v[166:169], v162
	ds_read_b128 v[170:173], v162 offset:1024
	ds_read_b128 v[174:177], v162 offset:2048
	ds_read_b128 v[182:185], v162 offset:3072
	ds_read_b128 v[188:191], v163
	ds_read_b128 v[192:195], v163 offset:1024
	ds_read_b128 v[196:199], v163 offset:2048
	ds_read_b128 v[200:203], v163 offset:3072
	ds_read_b128 v[204:207], v163 offset:4096
	ds_read_b128 v[208:211], v163 offset:5120
	ds_read_b128 v[212:215], v163 offset:6144
	ds_read_b128 v[216:219], v163 offset:7168
	s_add_u32 s58, s56, 0xfff84000
	s_addc_u32 s59, s57, -1
	s_cmp_eq_u32 s89, 28
	s_cselect_b32 s70, s19, s58
	s_cselect_b32 s71, s5, s59
	s_cselect_b32 s60, s47, s87
	s_cselect_b32 s61, s17, s88
	s_add_u32 s58, s70, 0x4000
	s_addc_u32 s59, s71, 0
	v_lshl_add_u64 v[178:179], s[56:57], 0, v[138:139]
	s_add_i32 m0, s72, 0xc000
	s_nop 0
	global_load_lds_dwordx4 v[178:179], off
	v_lshl_add_u64 v[178:179], s[56:57], 0, v[146:147]
	s_add_i32 m0, s72, 0xe000
	s_nop 0
	global_load_lds_dwordx4 v[178:179], off
	s_waitcnt vmcnt(8)
	s_waitcnt lgkmcnt(0)
	s_barrier
	s_setprio 1
	s_waitcnt lgkmcnt(0)
	v_mfma_f32_16x16x32_bf16 v[126:129], v[130:133], v[188:191], 0
	v_mfma_f32_16x16x32_bf16 v[126:129], v[134:137], v[192:195], v[126:129]
	v_mfma_f32_16x16x32_bf16 v[122:125], v[156:159], v[192:195], 0
	v_mfma_f32_16x16x32_bf16 v[122:125], v[152:155], v[188:191], v[122:125]
	v_mfma_f32_16x16x32_bf16 v[106:109], v[152:155], v[196:199], 0
	v_mfma_f32_16x16x32_bf16 v[106:109], v[156:159], v[200:203], v[106:109]
	v_mfma_f32_16x16x32_bf16 v[110:113], v[134:137], v[200:203], 0
	v_mfma_f32_16x16x32_bf16 v[110:113], v[130:133], v[196:199], v[110:113]
	v_mfma_f32_16x16x32_bf16 v[94:97], v[130:133], v[204:207], 0
	v_mfma_f32_16x16x32_bf16 v[94:97], v[134:137], v[208:211], v[94:97]
	v_mfma_f32_16x16x32_bf16 v[90:93], v[156:159], v[208:211], 0
	v_mfma_f32_16x16x32_bf16 v[90:93], v[152:155], v[204:207], v[90:93]
	v_mfma_f32_16x16x32_bf16 v[74:77], v[152:155], v[212:215], 0
	v_mfma_f32_16x16x32_bf16 v[74:77], v[156:159], v[216:219], v[74:77]
	v_mfma_f32_16x16x32_bf16 v[78:81], v[134:137], v[216:219], 0
	v_mfma_f32_16x16x32_bf16 v[78:81], v[130:133], v[212:215], v[78:81]
	s_setprio 0
	s_setprio 1
	v_mfma_f32_16x16x32_bf16 v[70:73], v[166:169], v[212:215], 0
	v_mfma_f32_16x16x32_bf16 v[70:73], v[170:173], v[216:219], v[70:73]
	v_mfma_f32_16x16x32_bf16 v[66:69], v[182:185], v[216:219], 0
	v_mfma_f32_16x16x32_bf16 v[66:69], v[174:177], v[212:215], v[66:69]
	v_mfma_f32_16x16x32_bf16 v[82:85], v[174:177], v[204:207], 0
	v_mfma_f32_16x16x32_bf16 v[82:85], v[182:185], v[208:211], v[82:85]
	v_mfma_f32_16x16x32_bf16 v[86:89], v[170:173], v[208:211], 0
	v_mfma_f32_16x16x32_bf16 v[86:89], v[166:169], v[204:207], v[86:89]
	v_mfma_f32_16x16x32_bf16 v[102:105], v[166:169], v[196:199], 0
	v_mfma_f32_16x16x32_bf16 v[102:105], v[170:173], v[200:203], v[102:105]
	v_mfma_f32_16x16x32_bf16 v[98:101], v[182:185], v[200:203], 0
	v_mfma_f32_16x16x32_bf16 v[98:101], v[174:177], v[196:199], v[98:101]
	v_mfma_f32_16x16x32_bf16 v[114:117], v[174:177], v[188:191], 0
	v_mfma_f32_16x16x32_bf16 v[114:117], v[182:185], v[192:195], v[114:117]
	v_mfma_f32_16x16x32_bf16 v[118:121], v[170:173], v[192:195], 0
	v_mfma_f32_16x16x32_bf16 v[118:121], v[166:169], v[188:191], v[118:121]
	s_setprio 0
	s_barrier
	ds_read_b128 v[188:191], v163 offset:16384
	ds_read_b128 v[192:195], v163 offset:17408
	ds_read_b128 v[196:199], v163 offset:18432
	ds_read_b128 v[200:203], v163 offset:19456
	ds_read_b128 v[204:207], v163 offset:20480
	ds_read_b128 v[208:211], v163 offset:21504
	ds_read_b128 v[212:215], v163 offset:22528
	ds_read_b128 v[216:219], v163 offset:23552
	s_add_i32 s90, s83, s15
	v_lshl_add_u64 v[178:179], s[60:61], 0, v[138:139]
	s_mov_b32 m0, s90
	s_nop 0
	global_load_lds_dwordx4 v[178:179], off
	s_add_i32 m0, s90, 0x2000
	s_add_u32 s90, s60, 0x80000
	v_lshl_add_u64 v[178:179], s[60:61], 0, v[140:141]
	s_addc_u32 s91, s61, 0
	s_add_i32 s92, s86, s15
	global_load_lds_dwordx4 v[178:179], off
	v_lshl_add_u64 v[178:179], s[90:91], 0, v[138:139]
	s_mov_b32 m0, s92
	s_nop 0
	global_load_lds_dwordx4 v[178:179], off
	v_lshl_add_u64 v[178:179], s[90:91], 0, v[140:141]
	s_add_i32 m0, s92, 0x2000
	s_nop 0
	global_load_lds_dwordx4 v[178:179], off
	v_lshl_add_u64 v[178:179], s[70:71], 0, v[138:139]
	s_mov_b32 m0, s72
	s_nop 0
	global_load_lds_dwordx4 v[178:179], off
	v_lshl_add_u64 v[178:179], s[70:71], 0, v[140:141]
	s_mov_b32 m0, s73
	s_nop 0
	global_load_lds_dwordx4 v[178:179], off
	s_waitcnt vmcnt(8)
	s_waitcnt lgkmcnt(0)
	s_barrier
; #define PG8_STAGE(bufoff, gbase, voff) do { _Pragma("unroll") for (int _i = 0; _i < 2; ++_i) \
;         __builtin_amdgcn_global_load_lds((const unsigned*)((const char*)(gbase) + (voff)[_i]), (PG8_LAS unsigned*)(lds + (bufoff) + ldsw + _i * 8192), 16, 0, 0); } while (0)
; #define PG8_LDA(dst, b, h) do { _Pragma("unroll") for (int m = 0; m < 4; ++m) _Pragma("unroll") for (int k = 0; k < 2; ++k) dst[m][k] = *(const PG8_LAS bf16x8*)(lds + PG8_SA(b, h) + aoff + m * 2048 + k * 1024); } while (0)
; #define PG8_LDB(dst, b, h) do { _Pragma("unroll") for (int n = 0; n < 2; ++n) _Pragma("unroll") for (int k = 0; k < 2; ++k) dst[n][k] = *(const PG8_LAS bf16x8*)(lds + PG8_SB(b, h) + boff + n * 2048 + k * 1024); } while (0)
; #define PG8_MMA(ai, bj, At, Bt) do { __builtin_amdgcn_s_setprio(1); _Pragma("unroll") for (int m = 0; m < 4; ++m) _Pragma("unroll") for (int n = 0; n < 2; ++n) _Pragma("unroll") for (int k = 0; k < 2; ++k) \
;         acc[ai][bj][m][n] = __builtin_amdgcn_mfma_f32_16x16x32_bf16(Bt[n][k], At[m][k], acc[ai][bj][m][n], 0, 0, 0); __builtin_amdgcn_s_setprio(0); } while (0)
; #define PG8_WAIT_V(n) asm volatile("s_waitcnt vmcnt(" #n ")" ::: "memory")
; #define PG8_WAIT_L(n) asm volatile("s_waitcnt lgkmcnt(" #n ")" ::: "memory")
; #define PG8_BAR __builtin_amdgcn_s_barrier()
; #define PG8_SCHED __builtin_amdgcn_sched_barrier(0)
; template <class Epi, class Sched, bool ALIGN_EPI = false, bool SP2 = false, bool RS = false, bool BPRE = false>
; __device__ __forceinline__ void gemm_phase(PG8_LAS unsigned char* lds, const Gemm g, const Sched& S, const Epi& E, const float* rs_ss = nullptr, PG8_LAS float* rs_tab = nullptr) {
;     ...
;             PG8_WAIT_V(8); PG8_WAIT_L(0); PG8_BAR; PG8_MMA(1, 0, At, B0); PG8_MMA(1, 1, At, B1); PG8_BAR; PG8_SCHED;
;             PG8_LDB(B0, 1, 0); PG8_LDB(B1, 1, 1); PG8_SCHED; PG8_LDA(At, 1, 0); PG8_STAGE(PG8_SA(0, 1), a2 + hstep, voffA);
;             PG8_WAIT_V(8); PG8_WAIT_L(0); PG8_BAR; PG8_MMA(0, 0, At, B0); PG8_MMA(0, 1, At, B1); PG8_BAR; PG8_SCHED;
	s_setprio 1
	s_waitcnt lgkmcnt(0)
	v_mfma_f32_16x16x32_bf16 v[62:65], v[130:133], v[188:191], 0
	v_mfma_f32_16x16x32_bf16 v[62:65], v[134:137], v[192:195], v[62:65]
	v_mfma_f32_16x16x32_bf16 v[58:61], v[156:159], v[192:195], 0
	v_mfma_f32_16x16x32_bf16 v[58:61], v[152:155], v[188:191], v[58:61]
	v_mfma_f32_16x16x32_bf16 v[42:45], v[152:155], v[196:199], 0
	v_mfma_f32_16x16x32_bf16 v[42:45], v[156:159], v[200:203], v[42:45]
	v_mfma_f32_16x16x32_bf16 v[46:49], v[134:137], v[200:203], 0
	v_mfma_f32_16x16x32_bf16 v[46:49], v[130:133], v[196:199], v[46:49]
	v_mfma_f32_16x16x32_bf16 v[30:33], v[130:133], v[204:207], 0
	v_mfma_f32_16x16x32_bf16 v[30:33], v[134:137], v[208:211], v[30:33]
	v_mfma_f32_16x16x32_bf16 v[26:29], v[156:159], v[208:211], 0
	v_mfma_f32_16x16x32_bf16 v[26:29], v[152:155], v[204:207], v[26:29]
	v_mfma_f32_16x16x32_bf16 v[10:13], v[152:155], v[212:215], 0
	v_mfma_f32_16x16x32_bf16 v[10:13], v[156:159], v[216:219], v[10:13]
	v_mfma_f32_16x16x32_bf16 v[14:17], v[134:137], v[216:219], 0
	v_mfma_f32_16x16x32_bf16 v[14:17], v[130:133], v[212:215], v[14:17]
	s_setprio 0
	s_setprio 1
	v_mfma_f32_16x16x32_bf16 v[6:9], v[166:169], v[212:215], 0
	v_mfma_f32_16x16x32_bf16 v[6:9], v[170:173], v[216:219], v[6:9]
	v_mfma_f32_16x16x32_bf16 v[2:5], v[182:185], v[216:219], 0
	v_mfma_f32_16x16x32_bf16 v[2:5], v[174:177], v[212:215], v[2:5]
	v_mfma_f32_16x16x32_bf16 v[18:21], v[174:177], v[204:207], 0
	v_mfma_f32_16x16x32_bf16 v[18:21], v[182:185], v[208:211], v[18:21]
	v_mfma_f32_16x16x32_bf16 v[22:25], v[170:173], v[208:211], 0
	v_mfma_f32_16x16x32_bf16 v[22:25], v[166:169], v[204:207], v[22:25]
	v_mfma_f32_16x16x32_bf16 v[38:41], v[166:169], v[196:199], 0
	v_mfma_f32_16x16x32_bf16 v[38:41], v[170:173], v[200:203], v[38:41]
	v_mfma_f32_16x16x32_bf16 v[34:37], v[182:185], v[200:203], 0
	v_mfma_f32_16x16x32_bf16 v[34:37], v[174:177], v[196:199], v[34:37]
	v_mfma_f32_16x16x32_bf16 v[50:53], v[174:177], v[188:191], 0
	v_mfma_f32_16x16x32_bf16 v[50:53], v[182:185], v[192:195], v[50:53]
	v_mfma_f32_16x16x32_bf16 v[54:57], v[170:173], v[192:195], 0
	v_mfma_f32_16x16x32_bf16 v[54:57], v[166:169], v[188:191], v[54:57]
	s_setprio 0
	s_barrier
	s_add_i32 s90, 0, 0x18000
	v_add_u32_e32 v143, s90, v160
	s_add_i32 s91, 0, 0x1c000
	ds_read_b128 v[130:133], v143
	ds_read_b128 v[134:137], v143 offset:1024
	ds_read_b128 v[152:155], v143 offset:2048
	ds_read_b128 v[156:159], v143 offset:3072
	v_add_u32_e32 v143, s91, v160
	ds_read_b128 v[166:169], v143
	ds_read_b128 v[170:173], v143 offset:1024
	ds_read_b128 v[174:177], v143 offset:2048
	ds_read_b128 v[182:185], v143 offset:3072
	ds_read_b128 v[188:191], v163 offset:32768
	ds_read_b128 v[192:195], v163 offset:33792
	ds_read_b128 v[196:199], v163 offset:34816
	ds_read_b128 v[200:203], v163 offset:35840
	ds_read_b128 v[204:207], v163 offset:36864
	ds_read_b128 v[208:211], v163 offset:37888
	ds_read_b128 v[212:215], v163 offset:38912
	ds_read_b128 v[216:219], v163 offset:39936
	s_add_u32 s70, s70, 0x80000
	s_addc_u32 s71, s71, 0
	s_mov_b32 m0, s74
	v_lshl_add_u64 v[178:179], s[70:71], 0, v[138:139]
	global_load_lds_dwordx4 v[178:179], off
	v_lshl_add_u64 v[178:179], s[70:71], 0, v[140:141]
	s_mov_b32 m0, s75
	s_nop 0
	global_load_lds_dwordx4 v[178:179], off
	s_waitcnt vmcnt(8)
	s_waitcnt lgkmcnt(0)
	s_barrier
	s_setprio 1
	s_waitcnt lgkmcnt(0)
	v_mfma_f32_16x16x32_bf16 v[126:129], v[130:133], v[188:191], v[126:129]
	v_mfma_f32_16x16x32_bf16 v[126:129], v[134:137], v[192:195], v[126:129]
	v_mfma_f32_16x16x32_bf16 v[122:125], v[156:159], v[192:195], v[122:125]
	v_mfma_f32_16x16x32_bf16 v[122:125], v[152:155], v[188:191], v[122:125]
	v_mfma_f32_16x16x32_bf16 v[106:109], v[152:155], v[196:199], v[106:109]
	v_mfma_f32_16x16x32_bf16 v[106:109], v[156:159], v[200:203], v[106:109]
	v_mfma_f32_16x16x32_bf16 v[110:113], v[134:137], v[200:203], v[110:113]
	v_mfma_f32_16x16x32_bf16 v[110:113], v[130:133], v[196:199], v[110:113]
	v_mfma_f32_16x16x32_bf16 v[94:97], v[130:133], v[204:207], v[94:97]
	v_mfma_f32_16x16x32_bf16 v[94:97], v[134:137], v[208:211], v[94:97]
	v_mfma_f32_16x16x32_bf16 v[90:93], v[156:159], v[208:211], v[90:93]
	v_mfma_f32_16x16x32_bf16 v[90:93], v[152:155], v[204:207], v[90:93]
	v_mfma_f32_16x16x32_bf16 v[74:77], v[152:155], v[212:215], v[74:77]
	v_mfma_f32_16x16x32_bf16 v[74:77], v[156:159], v[216:219], v[74:77]
	v_mfma_f32_16x16x32_bf16 v[78:81], v[134:137], v[216:219], v[78:81]
	v_mfma_f32_16x16x32_bf16 v[78:81], v[130:133], v[212:215], v[78:81]
	s_setprio 0
	s_setprio 1
	v_mfma_f32_16x16x32_bf16 v[70:73], v[166:169], v[212:215], v[70:73]
	v_mfma_f32_16x16x32_bf16 v[70:73], v[170:173], v[216:219], v[70:73]
	v_mfma_f32_16x16x32_bf16 v[66:69], v[182:185], v[216:219], v[66:69]
	v_mfma_f32_16x16x32_bf16 v[66:69], v[174:177], v[212:215], v[66:69]
	v_mfma_f32_16x16x32_bf16 v[82:85], v[174:177], v[204:207], v[82:85]
	v_mfma_f32_16x16x32_bf16 v[82:85], v[182:185], v[208:211], v[82:85]
	v_mfma_f32_16x16x32_bf16 v[86:89], v[170:173], v[208:211], v[86:89]
	v_mfma_f32_16x16x32_bf16 v[86:89], v[166:169], v[204:207], v[86:89]
	v_mfma_f32_16x16x32_bf16 v[102:105], v[166:169], v[196:199], v[102:105]
	v_mfma_f32_16x16x32_bf16 v[102:105], v[170:173], v[200:203], v[102:105]
	v_mfma_f32_16x16x32_bf16 v[98:101], v[182:185], v[200:203], v[98:101]
	v_mfma_f32_16x16x32_bf16 v[98:101], v[174:177], v[196:199], v[98:101]
	v_mfma_f32_16x16x32_bf16 v[114:117], v[174:177], v[188:191], v[114:117]
	v_mfma_f32_16x16x32_bf16 v[114:117], v[182:185], v[192:195], v[114:117]
	v_mfma_f32_16x16x32_bf16 v[118:121], v[170:173], v[192:195], v[118:121]
	v_mfma_f32_16x16x32_bf16 v[118:121], v[166:169], v[188:191], v[118:121]
	s_setprio 0
	s_barrier
; #define PG8_STAGE(bufoff, gbase, voff) do { _Pragma("unroll") for (int _i = 0; _i < 2; ++_i) \
;         __builtin_amdgcn_global_load_lds((const unsigned*)((const char*)(gbase) + (voff)[_i]), (PG8_LAS unsigned*)(lds + (bufoff) + ldsw + _i * 8192), 16, 0, 0); } while (0)
; #define PG8_LDA(dst, b, h) do { _Pragma("unroll") for (int m = 0; m < 4; ++m) _Pragma("unroll") for (int k = 0; k < 2; ++k) dst[m][k] = *(const PG8_LAS bf16x8*)(lds + PG8_SA(b, h) + aoff + m * 2048 + k * 1024); } while (0)
; #define PG8_LDB(dst, b, h) do { _Pragma("unroll") for (int n = 0; n < 2; ++n) _Pragma("unroll") for (int k = 0; k < 2; ++k) dst[n][k] = *(const PG8_LAS bf16x8*)(lds + PG8_SB(b, h) + boff + n * 2048 + k * 1024); } while (0)
; #define PG8_MMA(ai, bj, At, Bt) do { __builtin_amdgcn_s_setprio(1); _Pragma("unroll") for (int m = 0; m < 4; ++m) _Pragma("unroll") for (int n = 0; n < 2; ++n) _Pragma("unroll") for (int k = 0; k < 2; ++k) \
;         acc[ai][bj][m][n] = __builtin_amdgcn_mfma_f32_16x16x32_bf16(Bt[n][k], At[m][k], acc[ai][bj][m][n], 0, 0, 0); __builtin_amdgcn_s_setprio(0); } while (0)
; #define PG8_WAIT_V(n) asm volatile("s_waitcnt vmcnt(" #n ")" ::: "memory")
; #define PG8_WAIT_L(n) asm volatile("s_waitcnt lgkmcnt(" #n ")" ::: "memory")
; #define PG8_BAR __builtin_amdgcn_s_barrier()
; #define PG8_SCHED __builtin_amdgcn_sched_barrier(0)
; template <class Epi, class Sched, bool ALIGN_EPI = false, bool SP2 = false, bool RS = false, bool BPRE = false>
; __device__ __forceinline__ void gemm_phase(PG8_LAS unsigned char* lds, const Gemm g, const Sched& S, const Epi& E, const float* rs_ss = nullptr, PG8_LAS float* rs_tab = nullptr) {
;     ...
;             PG8_LDB(B0, 0, 0); PG8_LDB(B1, 0, 1); PG8_SCHED; PG8_LDA(At, 0, 0); PG8_STAGE(PG8_SA(1, 1), a1 + hstep, voffA);
;             PG8_WAIT_V(8); PG8_WAIT_L(0); PG8_BAR; PG8_MMA(0, 0, At, B0); PG8_MMA(0, 1, At, B1); PG8_BAR; PG8_SCHED;
;     ...
;             PG8_LDA(At, 1, 1); PG8_STAGE(PG8_SB(1, 0), b3, voffB); PG8_STAGE(PG8_SB(1, 1), b3 + hstep, voffB); PG8_STAGE(PG8_SA(1, 0), a3, voffA);
;             PG8_WAIT_V(8); PG8_WAIT_L(0); PG8_BAR; PG8_MMA(1, 0, At, B0); PG8_MMA(1, 1, At, B1); PG8_BAR; PG8_SCHED;
	ds_read_b128 v[188:191], v163 offset:49152
	ds_read_b128 v[192:195], v163 offset:50176
	ds_read_b128 v[196:199], v163 offset:51200
	ds_read_b128 v[200:203], v163 offset:52224
	ds_read_b128 v[204:207], v163 offset:53248
	ds_read_b128 v[208:211], v163 offset:54272
	ds_read_b128 v[212:215], v163 offset:55296
	ds_read_b128 v[216:219], v163 offset:56320
	s_add_u32 s70, s60, 0x4000
	s_addc_u32 s71, s61, 0
	s_add_i32 s90, s90, s15
	v_lshl_add_u64 v[178:179], s[70:71], 0, v[138:139]
	s_mov_b32 m0, s90
	s_nop 0
	global_load_lds_dwordx4 v[178:179], off
	s_add_i32 m0, s90, 0x2000
	s_add_u32 s60, s60, 0x84000
	v_lshl_add_u64 v[178:179], s[70:71], 0, v[140:141]
	s_addc_u32 s61, s61, 0
	s_add_i32 s70, s91, s15
	global_load_lds_dwordx4 v[178:179], off
	v_lshl_add_u64 v[178:179], s[60:61], 0, v[138:139]
	s_mov_b32 m0, s70
	s_nop 0
	global_load_lds_dwordx4 v[178:179], off
	v_lshl_add_u64 v[178:179], s[60:61], 0, v[140:141]
	s_add_i32 m0, s70, 0x2000
	s_nop 0
	global_load_lds_dwordx4 v[178:179], off
	v_lshl_add_u64 v[178:179], s[58:59], 0, v[138:139]
	s_mov_b32 m0, s79
	s_nop 0
	global_load_lds_dwordx4 v[178:179], off
	v_lshl_add_u64 v[178:179], s[58:59], 0, v[140:141]
	s_mov_b32 m0, s80
	s_nop 0
	global_load_lds_dwordx4 v[178:179], off
	s_waitcnt vmcnt(8)
	s_waitcnt lgkmcnt(0)
	s_barrier
	s_setprio 1
	s_waitcnt lgkmcnt(0)
	v_mfma_f32_16x16x32_bf16 v[62:65], v[130:133], v[188:191], v[62:65]
	v_mfma_f32_16x16x32_bf16 v[62:65], v[134:137], v[192:195], v[62:65]
	v_mfma_f32_16x16x32_bf16 v[58:61], v[156:159], v[192:195], v[58:61]
	v_mfma_f32_16x16x32_bf16 v[58:61], v[152:155], v[188:191], v[58:61]
	v_mfma_f32_16x16x32_bf16 v[42:45], v[152:155], v[196:199], v[42:45]
	v_mfma_f32_16x16x32_bf16 v[42:45], v[156:159], v[200:203], v[42:45]
	v_mfma_f32_16x16x32_bf16 v[46:49], v[134:137], v[200:203], v[46:49]
	v_mfma_f32_16x16x32_bf16 v[46:49], v[130:133], v[196:199], v[46:49]
	v_mfma_f32_16x16x32_bf16 v[30:33], v[130:133], v[204:207], v[30:33]
	v_mfma_f32_16x16x32_bf16 v[30:33], v[134:137], v[208:211], v[30:33]
	v_mfma_f32_16x16x32_bf16 v[26:29], v[156:159], v[208:211], v[26:29]
	v_mfma_f32_16x16x32_bf16 v[26:29], v[152:155], v[204:207], v[26:29]
	v_mfma_f32_16x16x32_bf16 v[10:13], v[152:155], v[212:215], v[10:13]
	v_mfma_f32_16x16x32_bf16 v[10:13], v[156:159], v[216:219], v[10:13]
	v_mfma_f32_16x16x32_bf16 v[14:17], v[134:137], v[216:219], v[14:17]
	v_mfma_f32_16x16x32_bf16 v[14:17], v[130:133], v[212:215], v[14:17]
	s_setprio 0
	s_setprio 1
	v_mfma_f32_16x16x32_bf16 v[6:9], v[166:169], v[212:215], v[6:9]
	v_mfma_f32_16x16x32_bf16 v[6:9], v[170:173], v[216:219], v[6:9]
	v_mfma_f32_16x16x32_bf16 v[2:5], v[182:185], v[216:219], v[2:5]
	v_mfma_f32_16x16x32_bf16 v[2:5], v[174:177], v[212:215], v[2:5]
	v_mfma_f32_16x16x32_bf16 v[18:21], v[174:177], v[204:207], v[18:21]
	v_mfma_f32_16x16x32_bf16 v[18:21], v[182:185], v[208:211], v[18:21]
	v_mfma_f32_16x16x32_bf16 v[22:25], v[170:173], v[208:211], v[22:25]
	v_mfma_f32_16x16x32_bf16 v[22:25], v[166:169], v[204:207], v[22:25]
	v_mfma_f32_16x16x32_bf16 v[38:41], v[166:169], v[196:199], v[38:41]
	v_mfma_f32_16x16x32_bf16 v[38:41], v[170:173], v[200:203], v[38:41]
	v_mfma_f32_16x16x32_bf16 v[34:37], v[182:185], v[200:203], v[34:37]
	v_mfma_f32_16x16x32_bf16 v[34:37], v[174:177], v[196:199], v[34:37]
	v_mfma_f32_16x16x32_bf16 v[50:53], v[174:177], v[188:191], v[50:53]
	v_mfma_f32_16x16x32_bf16 v[50:53], v[182:185], v[192:195], v[50:53]
	v_mfma_f32_16x16x32_bf16 v[54:57], v[170:173], v[192:195], v[54:57]
	v_mfma_f32_16x16x32_bf16 v[54:57], v[166:169], v[188:191], v[54:57]
	s_setprio 0
	s_barrier
	s_add_i32 s89, s89, 2
	s_add_u32 s56, s56, 0x8000
	s_addc_u32 s57, s57, 0
	s_add_u32 s87, s87, 0x8000
	s_addc_u32 s88, s88, 0
.LBB0_196:
	ds_read_b128 v[130:133], v161
	ds_read_b128 v[134:137], v161 offset:1024
	ds_read_b128 v[152:155], v161 offset:2048
	ds_read_b128 v[156:159], v161 offset:3072
	ds_read_b128 v[166:169], v162
	ds_read_b128 v[170:173], v162 offset:1024
	ds_read_b128 v[174:177], v162 offset:2048
	ds_read_b128 v[182:185], v162 offset:3072
	ds_read_b128 v[188:191], v163
	ds_read_b128 v[192:195], v163 offset:1024
	ds_read_b128 v[196:199], v163 offset:2048
	ds_read_b128 v[200:203], v163 offset:3072
	ds_read_b128 v[204:207], v163 offset:4096
	ds_read_b128 v[208:211], v163 offset:5120
	ds_read_b128 v[212:215], v163 offset:6144
	ds_read_b128 v[216:219], v163 offset:7168
	s_add_u32 s58, s56, 0xfff84000
	s_addc_u32 s59, s57, -1
	s_cmp_eq_u32 s89, 28
	s_cselect_b32 s70, s19, s58
	s_cselect_b32 s71, s5, s59
	s_cselect_b32 s60, s47, s87
	s_cselect_b32 s61, s17, s88
	s_add_u32 s58, s70, 0x4000
	s_addc_u32 s59, s71, 0
	v_lshl_add_u64 v[178:179], s[56:57], 0, v[138:139]
	s_add_i32 m0, s72, 0xc000
	s_nop 0
	global_load_lds_dwordx4 v[178:179], off
	v_lshl_add_u64 v[178:179], s[56:57], 0, v[146:147]
	s_add_i32 m0, s72, 0xe000
	s_nop 0
	global_load_lds_dwordx4 v[178:179], off
	s_waitcnt vmcnt(8)
	s_waitcnt lgkmcnt(0)
	s_barrier
; #define PG8_STAGE(bufoff, gbase, voff) do { _Pragma("unroll") for (int _i = 0; _i < 2; ++_i) \
;         __builtin_amdgcn_global_load_lds((const unsigned*)((const char*)(gbase) + (voff)[_i]), (PG8_LAS unsigned*)(lds + (bufoff) + ldsw + _i * 8192), 16, 0, 0); } while (0)
; #define PG8_LDA(dst, b, h) do { _Pragma("unroll") for (int m = 0; m < 4; ++m) _Pragma("unroll") for (int k = 0; k < 2; ++k) dst[m][k] = *(const PG8_LAS bf16x8*)(lds + PG8_SA(b, h) + aoff + m * 2048 + k * 1024); } while (0)
; #define PG8_MMA(ai, bj, At, Bt) do { __builtin_amdgcn_s_setprio(1); _Pragma("unroll") for (int m = 0; m < 4; ++m) _Pragma("unroll") for (int n = 0; n < 2; ++n) _Pragma("unroll") for (int k = 0; k < 2; ++k) \
;         acc[ai][bj][m][n] = __builtin_amdgcn_mfma_f32_16x16x32_bf16(Bt[n][k], At[m][k], acc[ai][bj][m][n], 0, 0, 0); __builtin_amdgcn_s_setprio(0); } while (0)
; #define PG8_WAIT_V(n) asm volatile("s_waitcnt vmcnt(" #n ")" ::: "memory")
; #define PG8_WAIT_L(n) asm volatile("s_waitcnt lgkmcnt(" #n ")" ::: "memory")
; #define PG8_BAR __builtin_amdgcn_s_barrier()
; #define PG8_SCHED __builtin_amdgcn_sched_barrier(0)
; template <class Epi, class Sched, bool ALIGN_EPI = false, bool SP2 = false, bool RS = false, bool BPRE = false>
; __device__ __forceinline__ void gemm_phase(PG8_LAS unsigned char* lds, const Gemm g, const Sched& S, const Epi& E, const float* rs_ss = nullptr, PG8_LAS float* rs_tab = nullptr) {
;     ...
;             PG8_WAIT_V(8); PG8_WAIT_L(0); PG8_BAR; PG8_MMA(0, 0, At, B0); PG8_MMA(0, 1, At, B1); PG8_BAR; PG8_SCHED;
;             PG8_LDA(At, 0, 1); PG8_STAGE(PG8_SB(0, 0), b2, voffB); PG8_STAGE(PG8_SB(0, 1), b2 + hstep, voffB); PG8_STAGE(PG8_SA(0, 0), a2, voffA);
;             PG8_WAIT_V(8); PG8_WAIT_L(0); PG8_BAR; PG8_MMA(1, 0, At, B0); PG8_MMA(1, 1, At, B1); PG8_BAR; PG8_SCHED;
	s_setprio 1
	s_waitcnt lgkmcnt(0)
	v_mfma_f32_16x16x32_bf16 v[126:129], v[130:133], v[188:191], v[126:129]
	v_mfma_f32_16x16x32_bf16 v[126:129], v[134:137], v[192:195], v[126:129]
	v_mfma_f32_16x16x32_bf16 v[122:125], v[156:159], v[192:195], v[122:125]
	v_mfma_f32_16x16x32_bf16 v[122:125], v[152:155], v[188:191], v[122:125]
	v_mfma_f32_16x16x32_bf16 v[106:109], v[152:155], v[196:199], v[106:109]
	v_mfma_f32_16x16x32_bf16 v[106:109], v[156:159], v[200:203], v[106:109]
	v_mfma_f32_16x16x32_bf16 v[110:113], v[134:137], v[200:203], v[110:113]
	v_mfma_f32_16x16x32_bf16 v[110:113], v[130:133], v[196:199], v[110:113]
	v_mfma_f32_16x16x32_bf16 v[94:97], v[130:133], v[204:207], v[94:97]
	v_mfma_f32_16x16x32_bf16 v[94:97], v[134:137], v[208:211], v[94:97]
	v_mfma_f32_16x16x32_bf16 v[90:93], v[156:159], v[208:211], v[90:93]
	v_mfma_f32_16x16x32_bf16 v[90:93], v[152:155], v[204:207], v[90:93]
	v_mfma_f32_16x16x32_bf16 v[74:77], v[152:155], v[212:215], v[74:77]
	v_mfma_f32_16x16x32_bf16 v[74:77], v[156:159], v[216:219], v[74:77]
	v_mfma_f32_16x16x32_bf16 v[78:81], v[134:137], v[216:219], v[78:81]
	v_mfma_f32_16x16x32_bf16 v[78:81], v[130:133], v[212:215], v[78:81]
	s_setprio 0
	s_setprio 1
	v_mfma_f32_16x16x32_bf16 v[70:73], v[166:169], v[212:215], v[70:73]
	v_mfma_f32_16x16x32_bf16 v[70:73], v[170:173], v[216:219], v[70:73]
	v_mfma_f32_16x16x32_bf16 v[66:69], v[182:185], v[216:219], v[66:69]
	v_mfma_f32_16x16x32_bf16 v[66:69], v[174:177], v[212:215], v[66:69]
	v_mfma_f32_16x16x32_bf16 v[82:85], v[174:177], v[204:207], v[82:85]
	v_mfma_f32_16x16x32_bf16 v[82:85], v[182:185], v[208:211], v[82:85]
	v_mfma_f32_16x16x32_bf16 v[86:89], v[170:173], v[208:211], v[86:89]
	v_mfma_f32_16x16x32_bf16 v[86:89], v[166:169], v[204:207], v[86:89]
	v_mfma_f32_16x16x32_bf16 v[102:105], v[166:169], v[196:199], v[102:105]
	v_mfma_f32_16x16x32_bf16 v[102:105], v[170:173], v[200:203], v[102:105]
	v_mfma_f32_16x16x32_bf16 v[98:101], v[182:185], v[200:203], v[98:101]
	v_mfma_f32_16x16x32_bf16 v[98:101], v[174:177], v[196:199], v[98:101]
	v_mfma_f32_16x16x32_bf16 v[114:117], v[174:177], v[188:191], v[114:117]
	v_mfma_f32_16x16x32_bf16 v[114:117], v[182:185], v[192:195], v[114:117]
	v_mfma_f32_16x16x32_bf16 v[118:121], v[170:173], v[192:195], v[118:121]
	v_mfma_f32_16x16x32_bf16 v[118:121], v[166:169], v[188:191], v[118:121]
	s_setprio 0
	s_barrier
	ds_read_b128 v[188:191], v163 offset:16384
	ds_read_b128 v[192:195], v163 offset:17408
	ds_read_b128 v[196:199], v163 offset:18432
	ds_read_b128 v[200:203], v163 offset:19456
	ds_read_b128 v[204:207], v163 offset:20480
	ds_read_b128 v[208:211], v163 offset:21504
	ds_read_b128 v[212:215], v163 offset:22528
	ds_read_b128 v[216:219], v163 offset:23552
	s_add_i32 s90, s83, s15
	v_lshl_add_u64 v[178:179], s[60:61], 0, v[138:139]
	s_mov_b32 m0, s90
	s_nop 0
	global_load_lds_dwordx4 v[178:179], off
	s_add_i32 m0, s90, 0x2000
	s_add_u32 s90, s60, 0x80000
	v_lshl_add_u64 v[178:179], s[60:61], 0, v[140:141]
	s_addc_u32 s91, s61, 0
	s_add_i32 s92, s86, s15
	global_load_lds_dwordx4 v[178:179], off
	v_lshl_add_u64 v[178:179], s[90:91], 0, v[138:139]
	s_mov_b32 m0, s92
	s_nop 0
	global_load_lds_dwordx4 v[178:179], off
	v_lshl_add_u64 v[178:179], s[90:91], 0, v[140:141]
	s_add_i32 m0, s92, 0x2000
	s_nop 0
	global_load_lds_dwordx4 v[178:179], off
	v_lshl_add_u64 v[178:179], s[70:71], 0, v[138:139]
	s_mov_b32 m0, s72
	s_nop 0
	global_load_lds_dwordx4 v[178:179], off
	v_lshl_add_u64 v[178:179], s[70:71], 0, v[140:141]
	s_mov_b32 m0, s73
	s_nop 0
	global_load_lds_dwordx4 v[178:179], off
	s_waitcnt vmcnt(8)
	s_waitcnt lgkmcnt(0)
	s_barrier
	s_setprio 1
	s_waitcnt lgkmcnt(0)
	v_mfma_f32_16x16x32_bf16 v[62:65], v[130:133], v[188:191], v[62:65]
	v_mfma_f32_16x16x32_bf16 v[62:65], v[134:137], v[192:195], v[62:65]
	v_mfma_f32_16x16x32_bf16 v[58:61], v[156:159], v[192:195], v[58:61]
	v_mfma_f32_16x16x32_bf16 v[58:61], v[152:155], v[188:191], v[58:61]
	v_mfma_f32_16x16x32_bf16 v[42:45], v[152:155], v[196:199], v[42:45]
	v_mfma_f32_16x16x32_bf16 v[42:45], v[156:159], v[200:203], v[42:45]
	v_mfma_f32_16x16x32_bf16 v[46:49], v[134:137], v[200:203], v[46:49]
	v_mfma_f32_16x16x32_bf16 v[46:49], v[130:133], v[196:199], v[46:49]
	v_mfma_f32_16x16x32_bf16 v[30:33], v[130:133], v[204:207], v[30:33]
	v_mfma_f32_16x16x32_bf16 v[30:33], v[134:137], v[208:211], v[30:33]
	v_mfma_f32_16x16x32_bf16 v[26:29], v[156:159], v[208:211], v[26:29]
	v_mfma_f32_16x16x32_bf16 v[26:29], v[152:155], v[204:207], v[26:29]
	v_mfma_f32_16x16x32_bf16 v[10:13], v[152:155], v[212:215], v[10:13]
	v_mfma_f32_16x16x32_bf16 v[10:13], v[156:159], v[216:219], v[10:13]
	v_mfma_f32_16x16x32_bf16 v[14:17], v[134:137], v[216:219], v[14:17]
	v_mfma_f32_16x16x32_bf16 v[14:17], v[130:133], v[212:215], v[14:17]
	s_setprio 0
	s_setprio 1
	v_mfma_f32_16x16x32_bf16 v[6:9], v[166:169], v[212:215], v[6:9]
	v_mfma_f32_16x16x32_bf16 v[6:9], v[170:173], v[216:219], v[6:9]
	v_mfma_f32_16x16x32_bf16 v[2:5], v[182:185], v[216:219], v[2:5]
	v_mfma_f32_16x16x32_bf16 v[2:5], v[174:177], v[212:215], v[2:5]
	v_mfma_f32_16x16x32_bf16 v[18:21], v[174:177], v[204:207], v[18:21]
	v_mfma_f32_16x16x32_bf16 v[18:21], v[182:185], v[208:211], v[18:21]
	v_mfma_f32_16x16x32_bf16 v[22:25], v[170:173], v[208:211], v[22:25]
	v_mfma_f32_16x16x32_bf16 v[22:25], v[166:169], v[204:207], v[22:25]
	v_mfma_f32_16x16x32_bf16 v[38:41], v[166:169], v[196:199], v[38:41]
	v_mfma_f32_16x16x32_bf16 v[38:41], v[170:173], v[200:203], v[38:41]
	v_mfma_f32_16x16x32_bf16 v[34:37], v[182:185], v[200:203], v[34:37]
	v_mfma_f32_16x16x32_bf16 v[34:37], v[174:177], v[196:199], v[34:37]
	v_mfma_f32_16x16x32_bf16 v[50:53], v[174:177], v[188:191], v[50:53]
	v_mfma_f32_16x16x32_bf16 v[50:53], v[182:185], v[192:195], v[50:53]
	v_mfma_f32_16x16x32_bf16 v[54:57], v[170:173], v[192:195], v[54:57]
	v_mfma_f32_16x16x32_bf16 v[54:57], v[166:169], v[188:191], v[54:57]
	s_setprio 0
	s_barrier
; #define PG8_STAGE(bufoff, gbase, voff) do { _Pragma("unroll") for (int _i = 0; _i < 2; ++_i) \
;         __builtin_amdgcn_global_load_lds((const unsigned*)((const char*)(gbase) + (voff)[_i]), (PG8_LAS unsigned*)(lds + (bufoff) + ldsw + _i * 8192), 16, 0, 0); } while (0)
; #define PG8_LDA(dst, b, h) do { _Pragma("unroll") for (int m = 0; m < 4; ++m) _Pragma("unroll") for (int k = 0; k < 2; ++k) dst[m][k] = *(const PG8_LAS bf16x8*)(lds + PG8_SA(b, h) + aoff + m * 2048 + k * 1024); } while (0)
; #define PG8_LDB(dst, b, h) do { _Pragma("unroll") for (int n = 0; n < 2; ++n) _Pragma("unroll") for (int k = 0; k < 2; ++k) dst[n][k] = *(const PG8_LAS bf16x8*)(lds + PG8_SB(b, h) + boff + n * 2048 + k * 1024); } while (0)
; #define PG8_MMA(ai, bj, At, Bt) do { __builtin_amdgcn_s_setprio(1); _Pragma("unroll") for (int m = 0; m < 4; ++m) _Pragma("unroll") for (int n = 0; n < 2; ++n) _Pragma("unroll") for (int k = 0; k < 2; ++k) \
;         acc[ai][bj][m][n] = __builtin_amdgcn_mfma_f32_16x16x32_bf16(Bt[n][k], At[m][k], acc[ai][bj][m][n], 0, 0, 0); __builtin_amdgcn_s_setprio(0); } while (0)
; #define PG8_WAIT_V(n) asm volatile("s_waitcnt vmcnt(" #n ")" ::: "memory")
; #define PG8_WAIT_L(n) asm volatile("s_waitcnt lgkmcnt(" #n ")" ::: "memory")
; #define PG8_BAR __builtin_amdgcn_s_barrier()
; #define PG8_SCHED __builtin_amdgcn_sched_barrier(0)
; template <class Epi, class Sched, bool ALIGN_EPI = false, bool SP2 = false, bool RS = false, bool BPRE = false>
; __device__ __forceinline__ void gemm_phase(PG8_LAS unsigned char* lds, const Gemm g, const Sched& S, const Epi& E, const float* rs_ss = nullptr, PG8_LAS float* rs_tab = nullptr) {
;     ...
;             PG8_LDB(B0, 1, 0); PG8_LDB(B1, 1, 1); PG8_SCHED; PG8_LDA(At, 1, 0); PG8_STAGE(PG8_SA(0, 1), a2 + hstep, voffA);
;             PG8_WAIT_V(8); PG8_WAIT_L(0); PG8_BAR; PG8_MMA(0, 0, At, B0); PG8_MMA(0, 1, At, B1); PG8_BAR; PG8_SCHED;
	s_add_i32 s90, 0, 0x18000
	v_add_u32_e32 v143, s90, v160
	s_add_i32 s91, 0, 0x1c000
	ds_read_b128 v[130:133], v143
	ds_read_b128 v[134:137], v143 offset:1024
	ds_read_b128 v[152:155], v143 offset:2048
	ds_read_b128 v[156:159], v143 offset:3072
	v_add_u32_e32 v143, s91, v160
	ds_read_b128 v[166:169], v143
	ds_read_b128 v[170:173], v143 offset:1024
	ds_read_b128 v[174:177], v143 offset:2048
	ds_read_b128 v[182:185], v143 offset:3072
	ds_read_b128 v[188:191], v163 offset:32768
	ds_read_b128 v[192:195], v163 offset:33792
	ds_read_b128 v[196:199], v163 offset:34816
	ds_read_b128 v[200:203], v163 offset:35840
	ds_read_b128 v[204:207], v163 offset:36864
	ds_read_b128 v[208:211], v163 offset:37888
	ds_read_b128 v[212:215], v163 offset:38912
	ds_read_b128 v[216:219], v163 offset:39936
	s_add_u32 s70, s70, 0x80000
	s_addc_u32 s71, s71, 0
	s_mov_b32 m0, s74
	v_lshl_add_u64 v[178:179], s[70:71], 0, v[138:139]
	global_load_lds_dwordx4 v[178:179], off
	v_lshl_add_u64 v[178:179], s[70:71], 0, v[140:141]
	s_mov_b32 m0, s75
	s_nop 0
	global_load_lds_dwordx4 v[178:179], off
	s_waitcnt vmcnt(8)
	s_waitcnt lgkmcnt(0)
	s_barrier
	s_setprio 1
	s_waitcnt lgkmcnt(0)
	v_mfma_f32_16x16x32_bf16 v[126:129], v[130:133], v[188:191], v[126:129]
	v_mfma_f32_16x16x32_bf16 v[126:129], v[134:137], v[192:195], v[126:129]
	v_mfma_f32_16x16x32_bf16 v[122:125], v[156:159], v[192:195], v[122:125]
	v_mfma_f32_16x16x32_bf16 v[122:125], v[152:155], v[188:191], v[122:125]
	v_mfma_f32_16x16x32_bf16 v[106:109], v[152:155], v[196:199], v[106:109]
	v_mfma_f32_16x16x32_bf16 v[106:109], v[156:159], v[200:203], v[106:109]
	v_mfma_f32_16x16x32_bf16 v[110:113], v[134:137], v[200:203], v[110:113]
	v_mfma_f32_16x16x32_bf16 v[110:113], v[130:133], v[196:199], v[110:113]
	v_mfma_f32_16x16x32_bf16 v[94:97], v[130:133], v[204:207], v[94:97]
	v_mfma_f32_16x16x32_bf16 v[94:97], v[134:137], v[208:211], v[94:97]
	v_mfma_f32_16x16x32_bf16 v[90:93], v[156:159], v[208:211], v[90:93]
	v_mfma_f32_16x16x32_bf16 v[90:93], v[152:155], v[204:207], v[90:93]
	v_mfma_f32_16x16x32_bf16 v[74:77], v[152:155], v[212:215], v[74:77]
	v_mfma_f32_16x16x32_bf16 v[74:77], v[156:159], v[216:219], v[74:77]
	v_mfma_f32_16x16x32_bf16 v[78:81], v[134:137], v[216:219], v[78:81]
	v_mfma_f32_16x16x32_bf16 v[78:81], v[130:133], v[212:215], v[78:81]
	s_setprio 0
	s_setprio 1
	v_mfma_f32_16x16x32_bf16 v[70:73], v[166:169], v[212:215], v[70:73]
	v_mfma_f32_16x16x32_bf16 v[70:73], v[170:173], v[216:219], v[70:73]
	v_mfma_f32_16x16x32_bf16 v[66:69], v[182:185], v[216:219], v[66:69]
	v_mfma_f32_16x16x32_bf16 v[66:69], v[174:177], v[212:215], v[66:69]
	v_mfma_f32_16x16x32_bf16 v[82:85], v[174:177], v[204:207], v[82:85]
	v_mfma_f32_16x16x32_bf16 v[82:85], v[182:185], v[208:211], v[82:85]
	v_mfma_f32_16x16x32_bf16 v[86:89], v[170:173], v[208:211], v[86:89]
	v_mfma_f32_16x16x32_bf16 v[86:89], v[166:169], v[204:207], v[86:89]
	v_mfma_f32_16x16x32_bf16 v[102:105], v[166:169], v[196:199], v[102:105]
	v_mfma_f32_16x16x32_bf16 v[102:105], v[170:173], v[200:203], v[102:105]
	v_mfma_f32_16x16x32_bf16 v[98:101], v[182:185], v[200:203], v[98:101]
	v_mfma_f32_16x16x32_bf16 v[98:101], v[174:177], v[196:199], v[98:101]
	v_mfma_f32_16x16x32_bf16 v[114:117], v[174:177], v[188:191], v[114:117]
	v_mfma_f32_16x16x32_bf16 v[114:117], v[182:185], v[192:195], v[114:117]
	v_mfma_f32_16x16x32_bf16 v[118:121], v[170:173], v[192:195], v[118:121]
	v_mfma_f32_16x16x32_bf16 v[118:121], v[166:169], v[188:191], v[118:121]
	s_setprio 0
	s_barrier
; #define PG8_STAGE(bufoff, gbase, voff) do { _Pragma("unroll") for (int _i = 0; _i < 2; ++_i) \
;         __builtin_amdgcn_global_load_lds((const unsigned*)((const char*)(gbase) + (voff)[_i]), (PG8_LAS unsigned*)(lds + (bufoff) + ldsw + _i * 8192), 16, 0, 0); } while (0)
; #define PG8_LDA(dst, b, h) do { _Pragma("unroll") for (int m = 0; m < 4; ++m) _Pragma("unroll") for (int k = 0; k < 2; ++k) dst[m][k] = *(const PG8_LAS bf16x8*)(lds + PG8_SA(b, h) + aoff + m * 2048 + k * 1024); } while (0)
; #define PG8_MMA(ai, bj, At, Bt) do { __builtin_amdgcn_s_setprio(1); _Pragma("unroll") for (int m = 0; m < 4; ++m) _Pragma("unroll") for (int n = 0; n < 2; ++n) _Pragma("unroll") for (int k = 0; k < 2; ++k) \
;         acc[ai][bj][m][n] = __builtin_amdgcn_mfma_f32_16x16x32_bf16(Bt[n][k], At[m][k], acc[ai][bj][m][n], 0, 0, 0); __builtin_amdgcn_s_setprio(0); } while (0)
; #define PG8_WAIT_V(n) asm volatile("s_waitcnt vmcnt(" #n ")" ::: "memory")
; #define PG8_WAIT_L(n) asm volatile("s_waitcnt lgkmcnt(" #n ")" ::: "memory")
; #define PG8_BAR __builtin_amdgcn_s_barrier()
; #define PG8_SCHED __builtin_amdgcn_sched_barrier(0)
; template <class Epi, class Sched, bool ALIGN_EPI = false, bool SP2 = false, bool RS = false, bool BPRE = false>
; __device__ __forceinline__ void gemm_phase(PG8_LAS unsigned char* lds, const Gemm g, const Sched& S, const Epi& E, const float* rs_ss = nullptr, PG8_LAS float* rs_tab = nullptr) {
;     ...
;             PG8_LDA(At, 1, 1); PG8_STAGE(PG8_SB(1, 0), b3, voffB); PG8_STAGE(PG8_SB(1, 1), b3 + hstep, voffB); PG8_STAGE(PG8_SA(1, 0), a3, voffA);
;             PG8_WAIT_V(8); PG8_WAIT_L(0); PG8_BAR; PG8_MMA(1, 0, At, B0); PG8_MMA(1, 1, At, B1); PG8_BAR; PG8_SCHED;
;     ...
;         if constexpr (ALIGN_EPI) { if (wr == 0) PG8_BAR; }
	ds_read_b128 v[188:191], v163 offset:49152
	ds_read_b128 v[192:195], v163 offset:50176
	ds_read_b128 v[196:199], v163 offset:51200
	ds_read_b128 v[200:203], v163 offset:52224
	ds_read_b128 v[204:207], v163 offset:53248
	ds_read_b128 v[208:211], v163 offset:54272
	ds_read_b128 v[212:215], v163 offset:55296
	ds_read_b128 v[216:219], v163 offset:56320
	s_add_u32 s70, s60, 0x4000
	s_addc_u32 s71, s61, 0
	s_add_i32 s90, s90, s15
	v_lshl_add_u64 v[178:179], s[70:71], 0, v[138:139]
	s_mov_b32 m0, s90
	s_nop 0
	global_load_lds_dwordx4 v[178:179], off
	s_add_i32 m0, s90, 0x2000
	s_add_u32 s60, s60, 0x84000
	v_lshl_add_u64 v[178:179], s[70:71], 0, v[140:141]
	s_addc_u32 s61, s61, 0
	s_add_i32 s70, s91, s15
	global_load_lds_dwordx4 v[178:179], off
	v_lshl_add_u64 v[178:179], s[60:61], 0, v[138:139]
	s_mov_b32 m0, s70
	s_nop 0
	global_load_lds_dwordx4 v[178:179], off
	v_lshl_add_u64 v[178:179], s[60:61], 0, v[140:141]
	s_add_i32 m0, s70, 0x2000
	s_nop 0
	global_load_lds_dwordx4 v[178:179], off
	v_lshl_add_u64 v[178:179], s[58:59], 0, v[138:139]
	s_mov_b32 m0, s79
	s_nop 0
	global_load_lds_dwordx4 v[178:179], off
	v_lshl_add_u64 v[178:179], s[58:59], 0, v[140:141]
	s_mov_b32 m0, s80
	s_nop 0
	global_load_lds_dwordx4 v[178:179], off
	s_waitcnt vmcnt(8)
	s_waitcnt lgkmcnt(0)
	s_barrier
	s_setprio 1
	s_waitcnt lgkmcnt(0)
	v_mfma_f32_16x16x32_bf16 v[62:65], v[130:133], v[188:191], v[62:65]
	v_mfma_f32_16x16x32_bf16 v[62:65], v[134:137], v[192:195], v[62:65]
	v_mfma_f32_16x16x32_bf16 v[58:61], v[156:159], v[192:195], v[58:61]
	v_mfma_f32_16x16x32_bf16 v[58:61], v[152:155], v[188:191], v[58:61]
	v_mfma_f32_16x16x32_bf16 v[42:45], v[152:155], v[196:199], v[42:45]
	v_mfma_f32_16x16x32_bf16 v[42:45], v[156:159], v[200:203], v[42:45]
	v_mfma_f32_16x16x32_bf16 v[46:49], v[134:137], v[200:203], v[46:49]
	v_mfma_f32_16x16x32_bf16 v[46:49], v[130:133], v[196:199], v[46:49]
	v_mfma_f32_16x16x32_bf16 v[30:33], v[130:133], v[204:207], v[30:33]
	v_mfma_f32_16x16x32_bf16 v[30:33], v[134:137], v[208:211], v[30:33]
	v_mfma_f32_16x16x32_bf16 v[26:29], v[156:159], v[208:211], v[26:29]
	v_mfma_f32_16x16x32_bf16 v[26:29], v[152:155], v[204:207], v[26:29]
	v_mfma_f32_16x16x32_bf16 v[10:13], v[152:155], v[212:215], v[10:13]
	v_mfma_f32_16x16x32_bf16 v[10:13], v[156:159], v[216:219], v[10:13]
	v_mfma_f32_16x16x32_bf16 v[14:17], v[134:137], v[216:219], v[14:17]
	v_mfma_f32_16x16x32_bf16 v[14:17], v[130:133], v[212:215], v[14:17]
	s_setprio 0
	s_setprio 1
	v_mfma_f32_16x16x32_bf16 v[6:9], v[166:169], v[212:215], v[6:9]
	v_mfma_f32_16x16x32_bf16 v[6:9], v[170:173], v[216:219], v[6:9]
	v_mfma_f32_16x16x32_bf16 v[2:5], v[182:185], v[216:219], v[2:5]
	v_mfma_f32_16x16x32_bf16 v[2:5], v[174:177], v[212:215], v[2:5]
	v_mfma_f32_16x16x32_bf16 v[18:21], v[174:177], v[204:207], v[18:21]
	v_mfma_f32_16x16x32_bf16 v[18:21], v[182:185], v[208:211], v[18:21]
	v_mfma_f32_16x16x32_bf16 v[22:25], v[170:173], v[208:211], v[22:25]
	v_mfma_f32_16x16x32_bf16 v[22:25], v[166:169], v[204:207], v[22:25]
	v_mfma_f32_16x16x32_bf16 v[38:41], v[166:169], v[196:199], v[38:41]
	v_mfma_f32_16x16x32_bf16 v[38:41], v[170:173], v[200:203], v[38:41]
	v_mfma_f32_16x16x32_bf16 v[34:37], v[182:185], v[200:203], v[34:37]
	v_mfma_f32_16x16x32_bf16 v[34:37], v[174:177], v[196:199], v[34:37]
	v_mfma_f32_16x16x32_bf16 v[50:53], v[174:177], v[188:191], v[50:53]
	v_mfma_f32_16x16x32_bf16 v[50:53], v[182:185], v[192:195], v[50:53]
	v_mfma_f32_16x16x32_bf16 v[54:57], v[170:173], v[192:195], v[54:57]
	v_mfma_f32_16x16x32_bf16 v[54:57], v[166:169], v[188:191], v[54:57]
	s_setprio 0
	s_barrier
	s_add_i32 s89, s89, 2
	s_add_u32 s56, s56, 0x8000
	s_addc_u32 s57, s57, 0
	s_add_u32 s87, s87, 0x8000
	s_addc_u32 s88, s88, 0
	s_cmp_gt_u32 s89, 29
	s_cbranch_scc0 .LBB0_196
	s_and_b64 vcc, exec, s[12:13]
	s_cbranch_vccz .LBB0_199
	s_barrier
